# speedup vs baseline: 1.0035x; 1.0035x over previous
;     ...
;     const int r = tid >> 4, c4 = (tid & 15) * 4;
; #pragma unroll
;     for (int i = 0; i < 2; ++i) {
;       float4 v = *(const float4*)(W + (long)(k0 + r + 32 * i) * N + n0 + c4);
;       float* d = lds + (r + 32 * i) * 65 + c4;
;       d[0] = v.x; d[1] = v.y; d[2] = v.z; d[3] = v.w;
;     }
;   }
;   __syncthreads();
;   {
;     const int n = tid >> 3, kq = (tid & 7) * 8;
;     float f[8];
; #pragma unroll
;     for (int j = 0; j < 8; ++j) f[j] = lds[(kq + j) * 65 + n];
;     if (gain) {
; #pragma unroll
;       for (int j = 0; j < 8; ++j) f[j] *= gain[k0 + kq + j];
;     }
;     u32x4 o = {pack2(f[0], f[1]), pack2(f[2], f[3]), pack2(f[4], f[5]), pack2(f[6], f[7])};
;     *(u32x4*)(Bt + (long)(n0 + n) * ldb + k0 + kq) = o;
;   }
;   __syncthreads();
; __device__ __forceinline__ void convert_weights(const Params& p, int l, char* shm, int wv) {
;     ...
;     else if (g < 2624) convert_tile(p.w_up + (long)l * 1024 * 4096, wb + O_UP, 1024, 4096, g - 1600, shm, p.mlp_g + l * DM, wv);
;     else convert_tile(p.w_down + (long)l * 4096 * 1024, wb + O_DOWN, 4096, 1024, g - 2624, shm, nullptr, wv);
.LBB0_795:
	s_add_i32 s71, s57, 0xa40
	s_cmpk_gt_i32 s71, 0x43f
	s_mov_b64 s[16:17], -1
	s_cbranch_scc0 .LBB0_815
	s_cmpk_gt_u32 s71, 0x4bf
	s_cbranch_scc0 .LBB0_812
	s_cmpk_gt_u32 s71, 0x53f
	s_cbranch_scc0 .LBB0_809
	s_cmpk_gt_u32 s71, 0x63f
	s_cbranch_scc0 .LBB0_806
	s_cmpk_gt_u32 s71, 0xa3f
	s_cbranch_scc0 .LBB0_801
	s_lshr_b32 s74, s57, 4
	s_lshl_b32 s16, s74, 10
	s_sub_i32 s16, s58, s16
	v_mbcnt_lo_u32_b32 v0, -1, 0
	v_mbcnt_hi_u32_b32 v0, -1, v0
	s_ashr_i32 s17, s16, 31
	v_add_u32_e32 v3, s84, v0
	s_lshl_b64 s[72:73], s[16:17], 2
	v_ashrrev_i32_e32 v7, 4, v3
	v_lshl_add_u32 v0, s74, 6, v7
	s_add_u32 s72, s20, s72
	v_lshlrev_b32_e32 v1, 4, v3
	s_addc_u32 s73, s21, s73
	v_and_b32_e32 v4, 0xf0, v1
	v_mov_b32_e32 v5, v2
	v_ashrrev_i32_e32 v1, 31, v0
	v_lshl_add_u64 v[8:9], s[72:73], 0, v[4:5]
	v_lshlrev_b64 v[0:1], 12, v[0:1]
	v_lshl_add_u64 v[0:1], v[8:9], 0, v[0:1]
	global_load_dwordx4 v[8:11], v[0:1], off
	s_movk_i32 s17, 0x104
	v_mad_u64_u32 v[4:5], s[72:73], v7, s17, v[4:5]
	v_add_co_u32_e32 v0, vcc, s87, v0
	v_ashrrev_i32_e32 v7, 3, v3
	s_nop 0
	v_addc_co_u32_e32 v1, vcc, 0, v1, vcc
	v_add_u32_e32 v5, 0x2080, v4
	s_mov_b32 s17, s52
	global_load_dwordx4 v[20:23], v[0:1], off
	s_waitcnt vmcnt(1)
	ds_write2_b32 v4, v8, v9 offset1:1
	ds_write2_b32 v4, v10, v11 offset0:2 offset1:3
	v_add_u32_e32 v0, 0x2088, v4
	s_waitcnt vmcnt(0)
	ds_write2_b32 v0, v22, v23 offset1:1
	v_lshlrev_b32_e32 v0, 3, v3
	v_and_b32_e32 v3, 56, v0
	v_mul_u32_u24_e32 v0, 0x104, v3
	ds_write2_b32 v5, v20, v21 offset1:1
	v_lshl_add_u32 v8, v7, 2, v0
	s_waitcnt lgkmcnt(0)
	s_barrier
	ds_read2_b32 v[0:1], v8 offset1:65
	ds_read2_b32 v[4:5], v8 offset0:130 offset1:195
	v_add_u32_e32 v8, 0x400, v8
	ds_read2_b32 v[10:11], v8 offset0:4 offset1:69
	ds_read2_b32 v[12:13], v8 offset0:134 offset1:199
	s_waitcnt lgkmcnt(3)
	v_cvt_pk_bf16_f32 v8, v0, v1
	v_add_u32_e32 v0, s16, v7
	v_ashrrev_i32_e32 v1, 31, v0
	v_lshlrev_b64 v[0:1], 13, v[0:1]
	v_lshl_add_u64 v[0:1], s[2:3], 0, v[0:1]
	s_lshl_b32 s16, s74, 7
	s_waitcnt lgkmcnt(2)
	v_cvt_pk_bf16_f32 v9, v4, v5
	v_lshl_add_u64 v[0:1], v[0:1], 0, s[16:17]
	v_lshlrev_b32_e32 v4, 1, v3
	v_mov_b32_e32 v5, v2
	s_waitcnt lgkmcnt(1)
	v_cvt_pk_bf16_f32 v10, v10, v11
	s_waitcnt lgkmcnt(0)
	v_cvt_pk_bf16_f32 v11, v12, v13
	v_lshl_add_u64 v[0:1], v[0:1], 0, v[4:5]
	global_store_dwordx4 v[0:1], v[8:11], off
	s_barrier
	s_mov_b64 s[16:17], 0
.LBB0_801:
	s_andn2_b64 vcc, exec, s[16:17]
	s_cbranch_vccnz .LBB0_805
	s_add_i32 s17, s58, 0x10000
	s_add_i32 s16, s57, 0x400
	s_and_b32 s17, s17, 0xfc0
	v_mbcnt_lo_u32_b32 v0, -1, 0
	v_mbcnt_hi_u32_b32 v0, -1, v0
	s_andn2_b32 s16, s16, 63
	v_add_u32_e32 v3, s84, v0
	s_lshl_b32 s72, s17, 2
	v_ashrrev_i32_e32 v7, 4, v3
	v_add_u32_e32 v0, s16, v7
	s_add_u32 s72, s22, s72
	v_lshlrev_b32_e32 v1, 4, v3
	s_addc_u32 s73, s23, 0
	v_and_b32_e32 v4, 0xf0, v1
	v_mov_b32_e32 v5, v2
	v_ashrrev_i32_e32 v1, 31, v0
	v_lshl_add_u64 v[8:9], s[72:73], 0, v[4:5]
	v_lshlrev_b64 v[0:1], 14, v[0:1]
	v_lshl_add_u64 v[0:1], v[8:9], 0, v[0:1]
	global_load_dwordx4 v[8:11], v[0:1], off
	s_movk_i32 s38, 0x104
	v_mad_u64_u32 v[4:5], s[72:73], v7, s38, v[4:5]
	s_mov_b32 s38, 0x80000
	v_add_co_u32_e32 v0, vcc, s38, v0
	v_ashrrev_i32_e32 v7, 3, v3
	s_nop 0
	v_addc_co_u32_e32 v1, vcc, 0, v1, vcc
	v_add_u32_e32 v5, 0x2080, v4
	v_readlane_b32 s38, v255, 16
	v_readlane_b32 s39, v255, 17
	s_andn2_b64 vcc, exec, s[38:39]
	global_load_dwordx4 v[20:23], v[0:1], off
	s_waitcnt vmcnt(1)
	ds_write2_b32 v4, v8, v9 offset1:1
	ds_write2_b32 v4, v10, v11 offset0:2 offset1:3
	v_add_u32_e32 v0, 0x2088, v4
	s_waitcnt vmcnt(0)
	ds_write2_b32 v0, v22, v23 offset1:1
	v_lshlrev_b32_e32 v0, 3, v3
	v_and_b32_e32 v3, 56, v0
	v_mul_u32_u24_e32 v0, 0x104, v3
	ds_write2_b32 v5, v20, v21 offset1:1
	v_lshl_add_u32 v8, v7, 2, v0
	v_add_u32_e32 v10, 0x400, v8
	s_waitcnt lgkmcnt(0)
	s_barrier
	ds_read2_b32 v[0:1], v8 offset1:65
	ds_read2_b32 v[4:5], v8 offset0:130 offset1:195
	ds_read2_b32 v[8:9], v10 offset0:4 offset1:69
	ds_read2_b32 v[10:11], v10 offset0:134 offset1:199
	s_cbranch_vccnz .LBB0_804
	v_or_b32_e32 v12, s16, v3
	v_mov_b32_e32 v13, v2
	v_lshl_add_u64 v[16:17], v[12:13], 2, s[12:13]
	global_load_dwordx4 v[12:15], v[16:17], off
	s_nop 0
	global_load_dwordx4 v[16:19], v[16:17], off offset:16
	s_waitcnt vmcnt(1) lgkmcnt(3)
	v_pk_mul_f32 v[0:1], v[0:1], v[12:13]
	s_waitcnt lgkmcnt(2)
	v_pk_mul_f32 v[4:5], v[4:5], v[14:15]
	s_waitcnt vmcnt(0) lgkmcnt(1)
	v_pk_mul_f32 v[8:9], v[8:9], v[16:17]
	s_waitcnt lgkmcnt(0)
	v_pk_mul_f32 v[10:11], v[10:11], v[18:19]

;     ...
;     const int r = tid >> 4, c4 = (tid & 15) * 4;
; #pragma unroll
;     for (int i = 0; i < 2; ++i) {
;       float4 v = *(const float4*)(W + (long)(k0 + r + 32 * i) * N + n0 + c4);
;       float* d = lds + (r + 32 * i) * 65 + c4;
;       d[0] = v.x; d[1] = v.y; d[2] = v.z; d[3] = v.w;
;     }
;   }
;   __syncthreads();
;   {
;     const int n = tid >> 3, kq = (tid & 7) * 8;
;     float f[8];
; #pragma unroll
;     for (int j = 0; j < 8; ++j) f[j] = lds[(kq + j) * 65 + n];
;     if (gain) {
; #pragma unroll
;       for (int j = 0; j < 8; ++j) f[j] *= gain[k0 + kq + j];
;     }
;     u32x4 o = {pack2(f[0], f[1]), pack2(f[2], f[3]), pack2(f[4], f[5]), pack2(f[6], f[7])};
;     *(u32x4*)(Bt + (long)(n0 + n) * ldb + k0 + kq) = o;
;   }
;   __syncthreads();
; __device__ __forceinline__ void convert_weights(const Params& p, int l, char* shm, int wv) {
;     ...
;     else if (g < 1600) convert_tile(p.w_out + (long)l * 1024 * 1024, wb + O_OUT, 1024, 1024, g - 1344, shm, nullptr, wv);
.LBB0_806:
	s_andn2_b64 vcc, exec, s[16:17]
	s_cbranch_vccnz .LBB0_808
	s_lshl_b32 s16, s59, 6
	s_and_b32 s17, s16, 0xfffffc00
	s_sub_i32 s17, s58, s17
	s_lshl_b32 s16, s57, 2
	s_add_i32 s72, s17, 0x14000
	s_addk_i32 s16, 0x1400
	v_mbcnt_lo_u32_b32 v0, -1, 0
	v_mbcnt_hi_u32_b32 v0, -1, v0
	s_ashr_i32 s73, s72, 31
	v_add_u32_e32 v3, s84, v0
	s_andn2_b32 s16, s16, 63
	s_lshl_b64 s[74:75], s[72:73], 2
	v_ashrrev_i32_e32 v7, 4, v3
	v_add_u32_e32 v0, s16, v7
	s_add_u32 s74, s24, s74
	v_lshlrev_b32_e32 v1, 4, v3
	s_addc_u32 s75, s25, s75
	v_and_b32_e32 v4, 0xf0, v1
	v_mov_b32_e32 v5, v2
	v_ashrrev_i32_e32 v1, 31, v0
	v_lshl_add_u64 v[8:9], s[74:75], 0, v[4:5]
	v_lshlrev_b64 v[0:1], 12, v[0:1]
	v_lshl_add_u64 v[0:1], v[8:9], 0, v[0:1]
	global_load_dwordx4 v[8:11], v[0:1], off
	s_movk_i32 s17, 0x104
	v_mad_u64_u32 v[4:5], s[74:75], v7, s17, v[4:5]
	v_add_co_u32_e32 v0, vcc, s87, v0
	v_ashrrev_i32_e32 v7, 3, v3
	s_nop 0
	v_addc_co_u32_e32 v1, vcc, 0, v1, vcc
	v_add_u32_e32 v5, 0x2080, v4
	s_mov_b32 s17, s52
	global_load_dwordx4 v[20:23], v[0:1], off
	s_waitcnt vmcnt(1)
	ds_write2_b32 v4, v8, v9 offset1:1
	ds_write2_b32 v4, v10, v11 offset0:2 offset1:3
	v_add_u32_e32 v0, 0x2088, v4
	s_waitcnt vmcnt(0)
	ds_write2_b32 v0, v22, v23 offset1:1
	v_lshlrev_b32_e32 v0, 3, v3
	v_and_b32_e32 v3, 56, v0
	v_mul_u32_u24_e32 v0, 0x104, v3
	ds_write2_b32 v5, v20, v21 offset1:1
	v_lshl_add_u32 v8, v7, 2, v0
	s_waitcnt lgkmcnt(0)
	s_barrier
	ds_read2_b32 v[0:1], v8 offset1:65
	ds_read2_b32 v[4:5], v8 offset0:130 offset1:195
	v_add_u32_e32 v8, 0x400, v8
	ds_read2_b32 v[10:11], v8 offset0:4 offset1:69
	ds_read2_b32 v[12:13], v8 offset0:134 offset1:199
	s_waitcnt lgkmcnt(3)
	v_cvt_pk_bf16_f32 v8, v0, v1
	v_add_u32_e32 v0, s72, v7
	v_ashrrev_i32_e32 v1, 31, v0
	v_lshlrev_b64 v[0:1], 11, v[0:1]
	v_lshl_add_u64 v[0:1], s[6:7], 0, v[0:1]
	s_waitcnt lgkmcnt(2)
	v_cvt_pk_bf16_f32 v9, v4, v5
	v_lshl_add_u64 v[0:1], s[16:17], 1, v[0:1]
	v_lshlrev_b32_e32 v4, 1, v3
	v_mov_b32_e32 v5, v2
	s_waitcnt lgkmcnt(1)
	v_cvt_pk_bf16_f32 v10, v10, v11
	s_waitcnt lgkmcnt(0)
	v_cvt_pk_bf16_f32 v11, v12, v13
	v_lshl_add_u64 v[0:1], v[0:1], 0, v[4:5]
	global_store_dwordx4 v[0:1], v[8:11], off
	s_barrier

;     ...
;     const int r = tid >> 4, c4 = (tid & 15) * 4;
; #pragma unroll
;     for (int i = 0; i < 2; ++i) {
;       float4 v = *(const float4*)(W + (long)(k0 + r + 32 * i) * N + n0 + c4);
;       float* d = lds + (r + 32 * i) * 65 + c4;
;       d[0] = v.x; d[1] = v.y; d[2] = v.z; d[3] = v.w;
;     }
;   }
;   __syncthreads();
;   {
;     const int n = tid >> 3, kq = (tid & 7) * 8;
;     float f[8];
; #pragma unroll
;     for (int j = 0; j < 8; ++j) f[j] = lds[(kq + j) * 65 + n];
;     if (gain) {
; #pragma unroll
;       for (int j = 0; j < 8; ++j) f[j] *= gain[k0 + kq + j];
;     }
;     u32x4 o = {pack2(f[0], f[1]), pack2(f[2], f[3]), pack2(f[4], f[5]), pack2(f[6], f[7])};
;     *(u32x4*)(Bt + (long)(n0 + n) * ldb + k0 + kq) = o;
;   }
;   __syncthreads();
; __device__ __forceinline__ void convert_weights(const Params& p, int l, char* shm, int wv) {
;     ...
;     else if (g < 1344) convert_tile(p.w_bswa + (long)l * 512 * 1024, wb + O_BSB + 512, 512, 1024, g - 1216, shm, nullptr, wv, 1024);
.LBB0_809:
	s_andn2_b64 vcc, exec, s[16:17]
	s_cbranch_vccnz .LBB0_811
	s_lshl_b32 s17, s65, 6
	s_and_b32 s17, s17, 0xfffffc00
	s_sub_i32 s17, s58, s17
	s_lshl_b32 s16, s57, 2
	s_add_i32 s72, s17, 0x16000
	s_addk_i32 s16, 0x1600
	v_mbcnt_lo_u32_b32 v0, -1, 0
	v_mbcnt_hi_u32_b32 v0, -1, v0
	s_ashr_i32 s73, s72, 31
	v_add_u32_e32 v3, s84, v0
	s_andn2_b32 s16, s16, 63
	s_lshl_b64 s[74:75], s[72:73], 2
	v_ashrrev_i32_e32 v7, 4, v3
	v_add_u32_e32 v0, s16, v7
	s_add_u32 s74, s26, s74
	v_lshlrev_b32_e32 v1, 4, v3
	s_addc_u32 s75, s27, s75
	v_and_b32_e32 v4, 0xf0, v1
	v_mov_b32_e32 v5, v2
	v_ashrrev_i32_e32 v1, 31, v0
	v_lshl_add_u64 v[8:9], s[74:75], 0, v[4:5]
	v_lshlrev_b64 v[0:1], 12, v[0:1]
	v_lshl_add_u64 v[0:1], v[8:9], 0, v[0:1]
	global_load_dwordx4 v[8:11], v[0:1], off
	s_movk_i32 s17, 0x104
	v_mad_u64_u32 v[4:5], s[74:75], v7, s17, v[4:5]
	v_add_co_u32_e32 v0, vcc, s87, v0
	v_ashrrev_i32_e32 v7, 3, v3
	s_nop 0
	v_addc_co_u32_e32 v1, vcc, 0, v1, vcc
	v_add_u32_e32 v5, 0x2080, v4
	s_mov_b32 s17, s52
	global_load_dwordx4 v[20:23], v[0:1], off
	s_waitcnt vmcnt(1)
	ds_write2_b32 v4, v8, v9 offset1:1
	ds_write2_b32 v4, v10, v11 offset0:2 offset1:3
	v_add_u32_e32 v0, 0x2088, v4
	s_waitcnt vmcnt(0)
	ds_write2_b32 v0, v22, v23 offset1:1
	v_lshlrev_b32_e32 v0, 3, v3
	v_and_b32_e32 v3, 56, v0
	v_mul_u32_u24_e32 v0, 0x104, v3
	ds_write2_b32 v5, v20, v21 offset1:1
	v_lshl_add_u32 v8, v7, 2, v0
	s_waitcnt lgkmcnt(0)
	s_barrier
	ds_read2_b32 v[0:1], v8 offset1:65
	ds_read2_b32 v[4:5], v8 offset0:130 offset1:195
	v_add_u32_e32 v8, 0x400, v8
	ds_read2_b32 v[10:11], v8 offset0:4 offset1:69
	ds_read2_b32 v[12:13], v8 offset0:134 offset1:199
	s_waitcnt lgkmcnt(3)
	v_cvt_pk_bf16_f32 v8, v0, v1
	v_add_u32_e32 v0, s72, v7
	v_ashrrev_i32_e32 v1, 31, v0
	v_lshlrev_b64 v[0:1], 11, v[0:1]
	v_lshl_add_u64 v[0:1], s[8:9], 0, v[0:1]
	s_waitcnt lgkmcnt(2)
	v_cvt_pk_bf16_f32 v9, v4, v5
	v_lshl_add_u64 v[0:1], s[16:17], 1, v[0:1]
	v_lshlrev_b32_e32 v4, 1, v3
	v_mov_b32_e32 v5, v2
	s_waitcnt lgkmcnt(1)
	v_cvt_pk_bf16_f32 v10, v10, v11
	s_waitcnt lgkmcnt(0)
	v_cvt_pk_bf16_f32 v11, v12, v13
	v_lshl_add_u64 v[0:1], v[0:1], 0, v[4:5]
	global_store_dwordx4 v[0:1], v[8:11], off
	s_barrier

;     ...
;     const int r = tid >> 4, c4 = (tid & 15) * 4;
; #pragma unroll
;     for (int i = 0; i < 2; ++i) {
;       float4 v = *(const float4*)(W + (long)(k0 + r + 32 * i) * N + n0 + c4);
;       float* d = lds + (r + 32 * i) * 65 + c4;
;       d[0] = v.x; d[1] = v.y; d[2] = v.z; d[3] = v.w;
;     }
;   }
;   __syncthreads();
;   {
;     const int n = tid >> 3, kq = (tid & 7) * 8;
;     float f[8];
; #pragma unroll
;     for (int j = 0; j < 8; ++j) f[j] = lds[(kq + j) * 65 + n];
;     if (gain) {
; #pragma unroll
;       for (int j = 0; j < 8; ++j) f[j] *= gain[k0 + kq + j];
;     }
;     u32x4 o = {pack2(f[0], f[1]), pack2(f[2], f[3]), pack2(f[4], f[5]), pack2(f[6], f[7])};
;     *(u32x4*)(Bt + (long)(n0 + n) * ldb + k0 + kq) = o;
;   }
;   __syncthreads();
; __device__ __forceinline__ void convert_weights(const Params& p, int l, char* shm, int wv) {
;     ...
;     else if (g < 1216) convert_tile(p.w_bsb + (long)l * 512 * 1024, wb + O_BSB, 512, 1024, g - 1088, shm, nullptr, wv, 1024);
.LBB0_812:
	s_andn2_b64 vcc, exec, s[16:17]
	s_cbranch_vccnz .LBB0_814
	s_lshl_b32 s16, s70, 6
	s_and_b32 s17, s16, 0xfffffc00
	s_sub_i32 s17, s58, s17
	s_lshl_b32 s16, s57, 2
	s_add_i32 s72, s17, 0x18000
	s_addk_i32 s16, 0x1800
	v_mbcnt_lo_u32_b32 v0, -1, 0
	v_mbcnt_hi_u32_b32 v0, -1, v0
	s_ashr_i32 s73, s72, 31
	v_add_u32_e32 v3, s84, v0
	s_andn2_b32 s16, s16, 63
	s_lshl_b64 s[74:75], s[72:73], 2
	v_ashrrev_i32_e32 v7, 4, v3
	v_add_u32_e32 v0, s16, v7
	s_add_u32 s74, s36, s74
	v_lshlrev_b32_e32 v1, 4, v3
	s_addc_u32 s75, s53, s75
	v_and_b32_e32 v4, 0xf0, v1
	v_mov_b32_e32 v5, v2
	v_ashrrev_i32_e32 v1, 31, v0
	v_lshl_add_u64 v[8:9], s[74:75], 0, v[4:5]
	v_lshlrev_b64 v[0:1], 12, v[0:1]
	v_lshl_add_u64 v[0:1], v[8:9], 0, v[0:1]
	global_load_dwordx4 v[8:11], v[0:1], off
	s_movk_i32 s17, 0x104
	v_mad_u64_u32 v[4:5], s[74:75], v7, s17, v[4:5]
	v_add_co_u32_e32 v0, vcc, s87, v0
	v_ashrrev_i32_e32 v7, 3, v3
	s_nop 0
	v_addc_co_u32_e32 v1, vcc, 0, v1, vcc
	v_add_u32_e32 v5, 0x2080, v4
	s_mov_b32 s17, s52
	global_load_dwordx4 v[20:23], v[0:1], off
	s_waitcnt vmcnt(1)
	ds_write2_b32 v4, v8, v9 offset1:1
	ds_write2_b32 v4, v10, v11 offset0:2 offset1:3
	v_add_u32_e32 v0, 0x2088, v4
	s_waitcnt vmcnt(0)
	ds_write2_b32 v0, v22, v23 offset1:1
	v_lshlrev_b32_e32 v0, 3, v3
	v_and_b32_e32 v3, 56, v0
	v_mul_u32_u24_e32 v0, 0x104, v3
	ds_write2_b32 v5, v20, v21 offset1:1
	v_lshl_add_u32 v8, v7, 2, v0
	s_waitcnt lgkmcnt(0)
	s_barrier
	ds_read2_b32 v[0:1], v8 offset1:65
	ds_read2_b32 v[4:5], v8 offset0:130 offset1:195
	v_add_u32_e32 v8, 0x400, v8
	ds_read2_b32 v[10:11], v8 offset0:4 offset1:69
	ds_read2_b32 v[12:13], v8 offset0:134 offset1:199
	s_waitcnt lgkmcnt(3)
	v_cvt_pk_bf16_f32 v8, v0, v1
	v_add_u32_e32 v0, s72, v7
	v_ashrrev_i32_e32 v1, 31, v0
	v_lshlrev_b64 v[0:1], 11, v[0:1]
	v_lshl_add_u64 v[0:1], s[10:11], 0, v[0:1]
	s_waitcnt lgkmcnt(2)
	v_cvt_pk_bf16_f32 v9, v4, v5
	v_lshl_add_u64 v[0:1], s[16:17], 1, v[0:1]
	v_lshlrev_b32_e32 v4, 1, v3
	v_mov_b32_e32 v5, v2
	s_waitcnt lgkmcnt(1)
	v_cvt_pk_bf16_f32 v10, v10, v11
	s_waitcnt lgkmcnt(0)
	v_cvt_pk_bf16_f32 v11, v12, v13
	v_lshl_add_u64 v[0:1], v[0:1], 0, v[4:5]
	global_store_dwordx4 v[0:1], v[8:11], off
	s_barrier

;     ...
;     const int r = tid >> 4, c4 = (tid & 15) * 4;
; #pragma unroll
;     for (int i = 0; i < 2; ++i) {
;       float4 v = *(const float4*)(W + (long)(k0 + r + 32 * i) * N + n0 + c4);
;       float* d = lds + (r + 32 * i) * 65 + c4;
;       d[0] = v.x; d[1] = v.y; d[2] = v.z; d[3] = v.w;
;     }
;   }
;   __syncthreads();
;   {
;     const int n = tid >> 3, kq = (tid & 7) * 8;
;     float f[8];
; #pragma unroll
;     for (int j = 0; j < 8; ++j) f[j] = lds[(kq + j) * 65 + n];
;     if (gain) {
; #pragma unroll
;       for (int j = 0; j < 8; ++j) f[j] *= gain[k0 + kq + j];
;     }
;     u32x4 o = {pack2(f[0], f[1]), pack2(f[2], f[3]), pack2(f[4], f[5]), pack2(f[6], f[7])};
;     *(u32x4*)(Bt + (long)(n0 + n) * ldb + k0 + kq) = o;
;   }
;   __syncthreads();
; __device__ __forceinline__ void convert_weights(const Params& p, int l, char* shm, int wv) {
;     ...
;     if (g < 1088) convert_tile(p.w_in + (long)l * 1024 * 4352, wb + O_IN, 1024, 4352, g, shm, p.mix_g + l * DM, wv);
.LBB0_815:
	s_andn2_b64 vcc, exec, s[16:17]
	s_cbranch_vccnz .LBB0_794
	s_mul_hi_i32 s16, s71, 0x78787879
	s_lshr_b32 s17, s16, 31
	s_ashr_i32 s16, s16, 5
	s_add_i32 s17, s16, s17
	s_mul_i32 s71, s17, 0xffffef00
	s_add_i32 s71, s58, s71
	s_add_i32 s72, s71, 0x29000
	s_ashr_i32 s73, s72, 31
	s_lshl_b32 s16, s17, 6
	v_mbcnt_lo_u32_b32 v0, -1, 0
	v_mbcnt_hi_u32_b32 v0, -1, v0
	s_lshl_b64 s[72:73], s[72:73], 2
	v_add_u32_e32 v3, s84, v0
	s_add_u32 s72, s54, s72
	v_lshlrev_b32_e32 v0, 4, v3
	v_ashrrev_i32_e32 v7, 4, v3
	s_addc_u32 s73, s55, s73
	v_and_b32_e32 v0, 0xf0, v0
	v_mov_b32_e32 v1, v2
	v_add_u32_e32 v12, s16, v7
	v_lshl_add_u64 v[4:5], s[72:73], 0, v[0:1]
	s_movk_i32 s42, 0x4400
	v_mad_i64_i32 v[8:9], s[72:73], v12, s42, v[4:5]
	global_load_dwordx4 v[8:11], v[8:9], off
	s_movk_i32 s39, 0x104
	v_mad_u64_u32 v[0:1], s[72:73], v7, s39, v[0:1]
	v_add_u32_e32 v1, 32, v12
	v_mad_i64_i32 v[4:5], s[72:73], v1, s42, v[4:5]
	v_add_u32_e32 v1, 0x2080, v0
	v_ashrrev_i32_e32 v7, 3, v3
	s_andn2_b64 vcc, exec, s[40:41]
	global_load_dwordx4 v[20:23], v[4:5], off
	s_waitcnt vmcnt(1)
	ds_write2_b32 v0, v8, v9 offset1:1
	ds_write2_b32 v0, v10, v11 offset0:2 offset1:3
	v_add_u32_e32 v0, 0x2088, v0
	s_waitcnt vmcnt(0)
	ds_write2_b32 v0, v22, v23 offset1:1
	v_lshlrev_b32_e32 v0, 3, v3
	v_and_b32_e32 v3, 56, v0
	v_mul_u32_u24_e32 v0, 0x104, v3
	ds_write2_b32 v1, v20, v21 offset1:1
	v_lshl_add_u32 v8, v7, 2, v0
	v_add_u32_e32 v10, 0x400, v8
	s_waitcnt lgkmcnt(0)
	s_barrier
	ds_read2_b32 v[0:1], v8 offset1:65
	ds_read2_b32 v[4:5], v8 offset0:130 offset1:195
	ds_read2_b32 v[8:9], v10 offset0:4 offset1:69
	ds_read2_b32 v[10:11], v10 offset0:134 offset1:199
	s_cbranch_vccnz .LBB0_793
	v_or_b32_e32 v12, s16, v3
	v_ashrrev_i32_e32 v13, 31, v12
	v_lshl_add_u64 v[16:17], v[12:13], 2, s[14:15]
	global_load_dwordx4 v[12:15], v[16:17], off
	s_nop 0
	global_load_dwordx4 v[16:19], v[16:17], off offset:16
	s_waitcnt vmcnt(1) lgkmcnt(3)
	v_pk_mul_f32 v[0:1], v[0:1], v[12:13]
	s_waitcnt lgkmcnt(2)
	v_pk_mul_f32 v[4:5], v[4:5], v[14:15]
	s_waitcnt vmcnt(0) lgkmcnt(1)
	v_pk_mul_f32 v[8:9], v[8:9], v[16:17]
	s_waitcnt lgkmcnt(0)
	v_pk_mul_f32 v[10:11], v[10:11], v[18:19]
	s_branch .LBB0_793
